# noprio + one static s_setprio 1 for waves 4-7 at kernel entry (doc recipe 6.3)
# speedup vs baseline: 1.0062x; 1.0062x over previous
; #define LAS __attribute__((address_space(3)))
; __device__ __forceinline__ unsigned xb_add(unsigned* p, unsigned v) { return __hip_atomic_fetch_add(p, v, __ATOMIC_RELAXED, __HIP_MEMORY_SCOPE_AGENT); }
; __device__ __forceinline__ unsigned xb_xcc_id() { return (unsigned)__builtin_amdgcn_s_getreg((3 << 11) | 20) & 0xFu; }
; __device__ __forceinline__ XcdBarrier xcd_barrier_post(unsigned* bar, volatile LAS unsigned* st) {
;     XcdBarrier b; b.bar = bar; b.x = xb_xcc_id(); b.st = st;
;     if (threadIdx.x == 0) (void)xb_add(&bar[XB_XCNT(b.x)], 1u);
;     return b;
; }
; __global__ void __launch_bounds__(512) mk_fwd(Args args) {
;     extern __shared__ __attribute__((aligned(16))) unsigned char lds_raw[];
;     Frame F;
;     F.lds = (LAS unsigned char*)lds_raw;
;     F.G = gridDim.x; F.bid = blockIdx.x;
;     F.in = args.in; F.out = args.out; F.ws = args.ws;
;     cg::grid_group grid = cg::this_grid();
;     volatile LAS unsigned* bst = (volatile LAS unsigned*)(F.lds + LDS_BARST);
;     if (threadIdx.x < 2) bst[threadIdx.x] = 0u;
;     __syncthreads();
;     const XcdBarrier bar = xcd_barrier_post((unsigned*)(args.ws + WS_BAR), bst);
_Z6mk_fwd4Args:
	v_readfirstlane_b32 s101, v0
	s_nop 3
	s_and_b32 s101, s101, 0x3ff
	s_lshr_b32 s101, s101, 6
	s_cmp_ge_u32 s101, 4
	s_cbranch_scc0 .Lmy_noprio
	s_setprio 1
.Lmy_noprio:
	s_load_dwordx8 s[64:71], s[0:1], 0xa0
	s_load_dwordx8 s[4:11], s[0:1], 0x80
	s_load_dword s92, s[0:1], 0xc8
	s_load_dwordx2 s[72:73], s[0:1], 0xc0
	s_add_u32 s14, s0, 0xc0
	v_and_b32_e32 v254, 0x3ff, v0
	s_addc_u32 s15, s1, 0
	v_cmp_gt_u32_e32 vcc, 2, v254
	s_and_saveexec_b64 s[12:13], vcc
	v_lshl_add_u32 v1, v254, 2, 0
	v_add_u32_e32 v1, 0x27f00, v1
	v_mov_b32_e32 v2, 0
	ds_write_b32 v1, v2
	s_or_b64 exec, exec, s[12:13]
	s_waitcnt lgkmcnt(0)
	s_barrier
	s_add_u32 s74, s68, 0xc0000
	s_getreg_b32 s3, hwreg(HW_REG_XCC_ID, 0, 4)
	s_addc_u32 s75, s69, 0
	s_and_b32 s33, s3, 15
	v_cmp_eq_u32_e64 s[16:17], 0, v254
	s_mov_b64 s[12:13], exec
	s_nop 0
	v_writelane_b32 v255, s16, 0
	s_nop 1
	v_writelane_b32 v255, s17, 1
	s_and_b64 s[16:17], s[12:13], s[16:17]
	s_mov_b64 exec, s[16:17]
	s_cbranch_execz .LBB0_5
	s_mov_b64 s[16:17], exec
	v_mbcnt_lo_u32_b32 v1, s16, 0
	v_mbcnt_hi_u32_b32 v1, s17, v1
	v_cmp_eq_u32_e32 vcc, 0, v1
	s_and_b64 s[18:19], exec, vcc
	s_mov_b64 exec, s[18:19]
	s_cbranch_execz .LBB0_5
	s_lshl_b32 s3, s33, 8
	s_bcnt1_i32_b64 s16, s[16:17]
	v_mov_b32_e32 v1, s3
	v_mov_b32_e32 v2, s16
	global_atomic_add v1, v2, s[74:75] offset:1024
